# scan producers: per-chunk throttle is one s_sleep instead of a run of s_nop (frees issue slots for the recurrence waves)
# baseline (speedup 1.0000x reference)
.Lp4_a_go:
	s_sleep 5
	s_or_b64 exec, exec, s[70:71]
	s_cmp_lt_u32 s78, 3
	s_cbranch_scc1 .Lp4_a_noyr
	s_mul_i32 s0, s87, 0x5100
	v_add3_u32 v131, v87, s0, v209
	ds_read_b32 v182, v131 offset:9216
	ds_read_b32 v183, v131 offset:9232
	ds_read_b32 v184, v131 offset:9248
	ds_read_b32 v185, v131 offset:9264
	ds_read_b32 v186, v131 offset:9280
	ds_read_b32 v187, v131 offset:9296
	ds_read_b32 v188, v131 offset:9312
	ds_read_b32 v189, v131 offset:9328
	ds_read_b32 v190, v131 offset:9344
	ds_read_b32 v191, v131 offset:9360
	ds_read_b32 v192, v131 offset:9376
	ds_read_b32 v193, v131 offset:9392
	ds_read_b32 v194, v131 offset:9408
	ds_read_b32 v195, v131 offset:9424
	ds_read_b32 v243, v131 offset:9440
	ds_read_b32 v147, v131 offset:9456
